# v54 + MLA K/V tiles staged by LDS-DMA (global_load_lds_dwordx4, per-lane source offsets reproduce the padded LDS images) instead of global_load + ds_write_b128
# speedup vs baseline: 1.0048x; 1.0048x over previous
; #define LAS __attribute__((address_space(3)))
; template <bool HASP, bool HASV>
; __device__ __forceinline__ void stage_load(Stage& st, const bf16_t* Kg, size_t ldk, const bf16_t* Pg, const bf16_t* Vg, size_t ldv, int tid) {
;     const int r0 = tid >> 4, c0 = (tid & 15) * 8;
;     st.k0 = *(const u32x4*)(Kg + (size_t)r0 * ldk + c0); st.k1 = *(const u32x4*)(Kg + (size_t)(r0 + 32) * ldk + c0);
;     if (HASP) st.kp = *(const u32x4*)(Pg + (size_t)(tid >> 3) * 64 + (tid & 7) * 8);
;     if (HASV) { st.v0 = *(const u32x4*)(Vg + (size_t)r0 * ldv + c0); st.v1 = *(const u32x4*)(Vg + (size_t)(r0 + 32) * ldv + c0); }
; }
; template <bool HASP, bool HASV>
; __device__ __forceinline__ void stage_store(const Stage& st, LAS unsigned char* kbuf, LAS unsigned char* vbuf, int tid) {
;     const int r0 = tid >> 4, c0 = (tid & 15) * 16;
;     *(LAS u32x4*)(kbuf + r0 * KP + c0) = st.k0; *(LAS u32x4*)(kbuf + (r0 + 32) * KP + c0) = st.k1;
;     if (HASP) *(LAS u32x4*)(kbuf + (tid >> 3) * KP + 256 + (tid & 7) * 16) = st.kp;
;     if (HASV) { *(LAS u32x4*)(vbuf + r0 * VP + c0) = st.v0; *(LAS u32x4*)(vbuf + (r0 + 32) * VP + c0) = st.v1; }
; }
; __device__ __forceinline__ void mla_unit(Frame& F, int b, int hd, int qb) {
;     ...
;     { const bf16_t* qrow = (const bf16_t*)(ws + WS_QMLA) + trow * 3072 + hd * 192 + 8 * hi;
; #pragma unroll
;       for (int d = 0; d < 12; ++d) qf[d] = *(const bf16x8*)(qrow + 16 * d); }
;     const bf16_t* KN = (const bf16_t*)(ws + WS_KN) + (size_t)b * S * 2048 + hd * 128; const bf16_t* VM = (const bf16_t*)(ws + WS_VM) + (size_t)b * S * 2048 + hd * 128;
;     const bf16_t* KPE = (const bf16_t*)(ws + WS_KPE) + (size_t)b * S * 64;
;     f32x16 O[4]; float m = -1e30f, l = 0.f; zero_o(O);
;     run_seq<M_MLA, 12>(lds, tid, qf, O, m, l, C, KN, 2048, KPE, VM, 2048, 0, 4 * qb + 3, 0ull, ts, -1, 0ull, 256 * qb + 32 * w + 31, 0.f, 0, 0);
.LBB0_961:
	s_xor_b64 s[92:93], s[0:1], -1
	s_and_b64 s[0:1], s[0:1], exec
	v_mov_b32_e32 v16, v0
	s_cselect_b32 s2, s94, s81
	v_readfirstlane_b32 s0, v16
	s_ashr_i32 s0, s0, 1
	s_lshl_b32 s97, s2, 8
	s_andn2_b32 s0, s0, 31
	v_and_b32_e32 v4, 31, v16
	s_add_i32 s3, s0, s97
	v_or_b32_e32 v170, s3, v4
	v_ashrrev_i32_e32 v171, 31, v170
	v_lshl_add_u64 v[172:173], s[72:73], 0, v[170:171]
	v_bfe_u32 v17, v16, 5, 1
	v_mad_u64_u32 v[2:3], s[0:1], v172, s75, v[168:169]
	v_mad_i32_i24 v3, v173, s75, v3
	v_lshlrev_b32_e32 v166, 4, v17
	v_lshl_add_u64 v[2:3], v[2:3], 0, v[166:167]
	global_load_dwordx4 v[98:101], v[2:3], off
	global_load_dwordx4 v[102:105], v[2:3], off offset:32
	global_load_dwordx4 v[106:109], v[2:3], off offset:64
	global_load_dwordx4 v[110:113], v[2:3], off offset:96
	global_load_dwordx4 v[114:117], v[2:3], off offset:128
	global_load_dwordx4 v[118:121], v[2:3], off offset:160
	global_load_dwordx4 v[122:125], v[2:3], off offset:192
	global_load_dwordx4 v[126:129], v[2:3], off offset:224
	global_load_dwordx4 v[130:133], v[2:3], off offset:256
	global_load_dwordx4 v[134:137], v[2:3], off offset:288
	global_load_dwordx4 v[138:141], v[2:3], off offset:320
	global_load_dwordx4 v[142:145], v[2:3], off offset:352
	v_mul_u32_u24_e32 v2, 0x190, v4
	v_add3_u32 v171, 0, v2, v166
	v_ashrrev_i32_e32 v2, 4, v16
	v_ashrrev_i32_e32 v3, 31, v2
	v_lshlrev_b64 v[4:5], 12, v[2:3]
	v_lshlrev_b32_e32 v3, 4, v16
	s_mov_b64 s[0:1], 0x20000
	v_lshl_add_u64 v[6:7], s[84:85], 0, v[4:5]
	v_and_b32_e32 v166, 0xf0, v3
	v_lshl_add_u64 v[8:9], v[4:5], 0, s[0:1]
	v_lshl_add_u64 v[6:7], v[6:7], 0, v[166:167]
	v_lshl_add_u64 v[10:11], s[84:85], 0, v[8:9]
	s_barrier
	v_readfirstlane_b32 s98, v0
	s_lshr_b32 s98, s98, 6
	s_movk_i32 s100, 0x5000
	s_mov_b32 s101, 0xe400
	s_movk_i32 s0, 0x1c0
	s_cmp_le_u32 s98, 4
	s_cselect_b32 s101, 0x10400, s101
	s_cselect_b32 s0, 0x3c0, s0
	v_add_u32_e32 v79, s0, v0
	s_cmp_eq_u32 s98, 0
	s_cselect_b32 s100, 0x6400, s100
	s_cselect_b64 s[0:1], -1, 0
	s_lshl_b32 s98, s98, 10
	s_add_i32 s101, s101, s98
	s_add_i32 s99, s98, 0xc400
	s_cmp_eq_u32 s98, 0
	s_cselect_b32 s99, 0x6000, s99
	v_mov_b32_e32 v76, s82
	v_mov_b32_e32 v77, s90
	v_add_u32_e32 v78, 0x38800000, v76
	v_add_u32_e32 v76, 0x34800000, v76
	v_add_u32_e32 v77, 0xffffdf00, v77
	v_mov_b32_e32 v74, 0x40000
	v_mov_b32_e32 v75, 0x2000
	v_mov_b32_e32 v67, v0
	v_mul_u32_u24_e32 v68, 0x51f, v67
	v_lshrrev_b32_e32 v68, 15, v68
	v_mul_u32_u24_e32 v69, 25, v68
	v_sub_u32_e32 v69, v67, v69
	v_lshlrev_b32_e32 v70, 12, v68
	v_lshlrev_b32_e32 v71, 4, v69
	v_cmp_gt_u32_e32 vcc, 16, v69
	v_cndmask_b32_e32 v71, 0, v71, vcc
	v_add3_u32 v70, v70, v71, v76
	v_lshlrev_b32_e32 v72, 7, v68
	v_lshl_add_u32 v72, v69, 4, v72
	v_add_u32_e32 v72, v72, v77
	v_add_u32_e32 v73, -16, v69
	v_cmp_gt_u32_e32 vcc, 8, v73
	v_cndmask_b32_e32 v146, v70, v72, vcc
	v_cndmask_b32_e32 v152, v74, v75, vcc
	v_add_u32_e32 v67, 512, v0
	v_mul_u32_u24_e32 v68, 0x51f, v67
	v_lshrrev_b32_e32 v68, 15, v68
	v_mul_u32_u24_e32 v69, 25, v68
	v_sub_u32_e32 v69, v67, v69
	v_lshlrev_b32_e32 v70, 12, v68
	v_lshlrev_b32_e32 v71, 4, v69
	v_cmp_gt_u32_e32 vcc, 16, v69
	v_cndmask_b32_e32 v71, 0, v71, vcc
	v_add3_u32 v70, v70, v71, v76
	v_lshlrev_b32_e32 v72, 7, v68
	v_lshl_add_u32 v72, v69, 4, v72
	v_add_u32_e32 v72, v72, v77
	v_add_u32_e32 v73, -16, v69
	v_cmp_gt_u32_e32 vcc, 8, v73
	v_cndmask_b32_e32 v147, v70, v72, vcc
	v_cndmask_b32_e32 v153, v74, v75, vcc
	v_add_u32_e32 v67, 1024, v0
	v_mul_u32_u24_e32 v68, 0x51f, v67
	v_lshrrev_b32_e32 v68, 15, v68
	v_mul_u32_u24_e32 v69, 25, v68
	v_sub_u32_e32 v69, v67, v69
	v_lshlrev_b32_e32 v70, 12, v68
	v_lshlrev_b32_e32 v71, 4, v69
	v_cmp_gt_u32_e32 vcc, 16, v69
	v_cndmask_b32_e32 v71, 0, v71, vcc
	v_add3_u32 v70, v70, v71, v76
	v_lshlrev_b32_e32 v72, 7, v68
	v_lshl_add_u32 v72, v69, 4, v72
	v_add_u32_e32 v72, v72, v77
	v_add_u32_e32 v73, -16, v69
	v_cmp_gt_u32_e32 vcc, 8, v73
	v_cndmask_b32_e32 v148, v70, v72, vcc
	v_cndmask_b32_e32 v154, v74, v75, vcc
	v_add_u32_e32 v67, 1536, v0
	v_mul_u32_u24_e32 v68, 0x51f, v67
	v_lshrrev_b32_e32 v68, 15, v68
	v_mul_u32_u24_e32 v69, 25, v68
	v_sub_u32_e32 v69, v67, v69
	v_lshlrev_b32_e32 v70, 12, v68
	v_lshlrev_b32_e32 v71, 4, v69
	v_cmp_gt_u32_e32 vcc, 16, v69
	v_cndmask_b32_e32 v71, 0, v71, vcc
	v_add3_u32 v70, v70, v71, v76
	v_lshlrev_b32_e32 v72, 7, v68
	v_lshl_add_u32 v72, v69, 4, v72
	v_add_u32_e32 v72, v72, v77
	v_add_u32_e32 v73, -16, v69
	v_cmp_gt_u32_e32 vcc, 8, v73
	v_cndmask_b32_e32 v80, v70, v72, vcc
	v_cndmask_b32_e32 v81, v74, v75, vcc
	v_add_u32_e32 v67, -64, v0
	v_mul_u32_u24_e32 v68, 0xccd, v67
	v_lshrrev_b32_e32 v68, 16, v68
	v_mul_u32_u24_e32 v69, 20, v68
	v_sub_u32_e32 v69, v67, v69
	v_lshlrev_b32_e32 v70, 12, v68
	v_lshlrev_b32_e32 v71, 4, v69
	v_cmp_gt_u32_e32 vcc, 16, v69
	v_cndmask_b32_e32 v71, 0, v71, vcc
	v_add3_u32 v82, v70, v71, v78
; #define LAS __attribute__((address_space(3)))
; template <bool HASP, bool HASV>
; __device__ __forceinline__ void stage_load(Stage& st, const bf16_t* Kg, size_t ldk, const bf16_t* Pg, const bf16_t* Vg, size_t ldv, int tid) {
;     const int r0 = tid >> 4, c0 = (tid & 15) * 8;
;     st.k0 = *(const u32x4*)(Kg + (size_t)r0 * ldk + c0); st.k1 = *(const u32x4*)(Kg + (size_t)(r0 + 32) * ldk + c0);
;     if (HASP) st.kp = *(const u32x4*)(Pg + (size_t)(tid >> 3) * 64 + (tid & 7) * 8);
;     if (HASV) { st.v0 = *(const u32x4*)(Vg + (size_t)r0 * ldv + c0); st.v1 = *(const u32x4*)(Vg + (size_t)(r0 + 32) * ldv + c0); }
; }
; template <bool HASP, bool HASV>
; __device__ __forceinline__ void stage_store(const Stage& st, LAS unsigned char* kbuf, LAS unsigned char* vbuf, int tid) {
;     const int r0 = tid >> 4, c0 = (tid & 15) * 16;
;     *(LAS u32x4*)(kbuf + r0 * KP + c0) = st.k0; *(LAS u32x4*)(kbuf + (r0 + 32) * KP + c0) = st.k1;
;     if (HASP) *(LAS u32x4*)(kbuf + (tid >> 3) * KP + 256 + (tid & 7) * 16) = st.kp;
;     if (HASV) { *(LAS u32x4*)(vbuf + r0 * VP + c0) = st.v0; *(LAS u32x4*)(vbuf + (r0 + 32) * VP + c0) = st.v1; }
; }
; template <int MODE, int NQ> ...
;     ...
;     __syncthreads();
;     if (j >= 0) stage_load<HASP, HASV>(st, Kg + (size_t)j * 64 * ldk, ldk, Pg + (size_t)j * 64 * 64, Vg + (size_t)j * 64 * ldv, ldv, tid);
;     int it = 0;
;     while (j >= 0) {
;         const int bsel = it & 1;
;         stage_store<HASP, HASV>(st, lds + OFF_K + bsel * KBUF, lds + OFF_V + bsel * VBUF, tid);
;         __syncthreads();
;         int jn;
;         if (MODE == M_SEL) { jn = rem ? (int)__builtin_ctzll(rem) : -1; rem &= rem - 1ull; } else { jn = (j + 1 <= jhi) ? j + 1 : -1; }
;         if (jn >= 0) stage_load<HASP, HASV>(st, Kg + (size_t)jn * 64 * ldk, ldk, Pg + (size_t)jn * 64 * 64, Vg + (size_t)jn * 64 * ldv, ldv, tid);
	v_cndmask_b32_e64 v149, v82, v80, s[0:1]
	v_cndmask_b32_e64 v155, v74, v81, s[0:1]
	v_add_u32_e32 v67, 0x1c0, v0
	v_mul_u32_u24_e32 v68, 0xccd, v67
	v_lshrrev_b32_e32 v68, 16, v68
	v_mul_u32_u24_e32 v69, 20, v68
	v_sub_u32_e32 v69, v67, v69
	v_lshlrev_b32_e32 v70, 12, v68
	v_lshlrev_b32_e32 v71, 4, v69
	v_cmp_gt_u32_e32 vcc, 16, v69
	v_cndmask_b32_e32 v71, 0, v71, vcc
	v_add3_u32 v150, v70, v71, v78
	v_mov_b32_e32 v67, v79
	v_mul_u32_u24_e32 v68, 0xccd, v67
	v_lshrrev_b32_e32 v68, 16, v68
	v_mul_u32_u24_e32 v69, 20, v68
	v_sub_u32_e32 v69, v67, v69
	v_lshlrev_b32_e32 v70, 12, v68
	v_lshlrev_b32_e32 v71, 4, v69
	v_cmp_gt_u32_e32 vcc, 16, v69
	v_cndmask_b32_e32 v71, 0, v71, vcc
	v_add3_u32 v151, v70, v71, v78
	s_mov_b32 m0, s98
	s_nop 0
	global_load_lds_dwordx4 v146, s[30:31]
	s_add_i32 m0, s98, 0x2000
	v_add_u32_e32 v146, v146, v152
	global_load_lds_dwordx4 v147, s[30:31]
	s_add_i32 m0, s98, 0x4000
	v_add_u32_e32 v147, v147, v153
	global_load_lds_dwordx4 v148, s[30:31]
	s_mov_b32 m0, s99
	v_add_u32_e32 v148, v148, v154
	global_load_lds_dwordx4 v149, s[30:31]
	s_add_i32 m0, s98, 0xe400
	v_add_u32_e32 v149, v149, v155
	global_load_lds_dwordx4 v150, s[30:31]
	s_mov_b32 m0, s101
	v_add_u32_e32 v150, 0x40000, v150
	global_load_lds_dwordx4 v151, s[30:31]
	v_add_u32_e32 v151, 0x40000, v151
	v_lshl_add_u64 v[10:11], v[10:11], 0, v[166:167]
	v_ashrrev_i32_e32 v6, 3, v16
	v_ashrrev_i32_e32 v7, 31, v6
	v_lshlrev_b64 v[10:11], 7, v[6:7]
	v_lshl_add_u64 v[12:13], s[88:89], 0, v[10:11]
	v_and_b32_e32 v176, 0x70, v3
	v_mov_b32_e32 v177, v167
	v_lshl_add_u64 v[8:9], s[86:87], 0, v[8:9]
	v_lshl_add_u64 v[12:13], v[12:13], 0, v[176:177]
	v_lshl_add_u64 v[14:15], s[86:87], 0, v[4:5]
	v_lshl_add_u64 v[8:9], v[8:9], 0, v[166:167]
	v_lshl_add_u64 v[14:15], v[14:15], 0, v[166:167]
	v_lshlrev_b32_e32 v174, 2, v17
	v_lshrrev_b32_e32 v3, 2, v16
	v_and_b32_e32 v7, 16, v16
	v_lshlrev_b32_e32 v8, 2, v16
	s_lshl_b32 s0, s2, 2
	v_and_or_b32 v3, v3, 3, v174
	v_and_or_b32 v7, v8, 12, v7
	s_or_b32 s95, s0, 3
	v_mul_u32_u24_e32 v3, 0x140, v3
	v_lshlrev_b32_e32 v7, 1, v7
	v_mul_lo_u32 v183, v6, s76
	s_movk_i32 s0, 0x140
	v_and_b32_e32 v6, 7, v16
	v_add3_u32 v175, 0, v3, v7
	v_mul_lo_u32 v177, v2, s76
	v_mul_lo_u32 v184, v2, s0
	v_lshl_add_u64 v[2:3], s[90:91], 0, v[10:11]
	v_lshlrev_b32_e32 v6, 4, v6
	v_mov_b32_e32 v7, v167
	v_lshl_add_u64 v[178:179], v[2:3], 0, v[6:7]
	v_lshl_add_u64 v[2:3], s[82:83], 0, v[4:5]
	v_and_b32_e32 v4, 15, v16
	v_lshlrev_b32_e32 v4, 4, v4
	v_mov_b32_e32 v5, v167
	v_mov_b32_e32 v16, v167
	v_mov_b32_e32 v17, v167
	v_lshl_add_u64 v[180:181], v[2:3], 0, v[4:5]
	v_mov_b32_e32 v2, v167
	v_mov_b32_e32 v3, v167
	v_mov_b32_e32 v4, v167
	v_mov_b32_e32 v6, v167
	v_mov_b32_e32 v8, v167
	v_mov_b32_e32 v9, v167
	v_mov_b32_e32 v10, v167
	v_mov_b32_e32 v11, v167
	v_mov_b32_e32 v12, v167
	v_mov_b32_e32 v13, v167
	v_mov_b32_e32 v14, v167
	v_mov_b32_e32 v15, v167
	v_mov_b64_e32 v[32:33], v[16:17]
	v_mov_b64_e32 v[48:49], v[16:17]
	v_mov_b64_e32 v[64:65], v[16:17]
	s_or_b32 s96, s3, 31
	v_add_u32_e32 v182, 0x3200, v177
	v_add_u32_e32 v185, 0x2800, v184
	s_addk_i32 s97, 0x100
	v_sub_u32_e32 v187, v170, v174
	s_mov_b32 s33, 0
	v_mov_b32_e32 v188, 0
	v_mov_b32_e32 v190, 0xf149f2ca
	v_mov_b64_e32 v[30:31], v[14:15]
	v_mov_b64_e32 v[28:29], v[12:13]
	v_mov_b64_e32 v[26:27], v[10:11]
	v_mov_b64_e32 v[24:25], v[8:9]
	v_mov_b64_e32 v[22:23], v[6:7]
	v_mov_b64_e32 v[20:21], v[4:5]
	v_mov_b64_e32 v[18:19], v[2:3]
	v_mov_b64_e32 v[46:47], v[14:15]
	v_mov_b64_e32 v[44:45], v[12:13]
	v_mov_b64_e32 v[42:43], v[10:11]
	v_mov_b64_e32 v[40:41], v[8:9]
	v_mov_b64_e32 v[38:39], v[6:7]
	v_mov_b64_e32 v[36:37], v[4:5]
	v_mov_b64_e32 v[34:35], v[2:3]
	v_mov_b64_e32 v[62:63], v[14:15]
	v_mov_b64_e32 v[60:61], v[12:13]
	v_mov_b64_e32 v[58:59], v[10:11]
	v_mov_b64_e32 v[56:57], v[8:9]
	v_mov_b64_e32 v[54:55], v[6:7]
	v_mov_b64_e32 v[52:53], v[4:5]
	v_mov_b64_e32 v[50:51], v[2:3]
	s_mov_b32 s64, 0
.LBB0_962:
	s_and_b32 s65, s64, 1
	s_mul_i32 s0, s65, 0x6400
	s_waitcnt vmcnt(0) lgkmcnt(0)
	s_barrier
	s_cmp_ge_u32 s64, s95
	s_cbranch_scc1 .LBB0_964
	s_xor_b32 s1, s65, 1
	s_mul_i32 s2, s1, 0x5000
	s_mul_i32 vcc_lo, s1, s100
	s_mul_i32 s1, s1, 0x6400
	s_add_i32 m0, s98, s1
	s_add_i32 vcc_hi, s98, 0x2000
	global_load_lds_dwordx4 v146, s[30:31]
	s_add_i32 m0, vcc_hi, s1
	v_add_u32_e32 v146, v146, v152
	global_load_lds_dwordx4 v147, s[30:31]
	s_add_i32 vcc_hi, s98, 0x4000
	s_add_i32 m0, vcc_hi, s1
	v_add_u32_e32 v147, v147, v153
	global_load_lds_dwordx4 v148, s[30:31]
	s_add_i32 m0, s99, vcc_lo
	v_add_u32_e32 v148, v148, v154
	global_load_lds_dwordx4 v149, s[30:31]
	s_add_i32 vcc_hi, s98, 0xe400
	s_add_i32 m0, vcc_hi, s2
	v_add_u32_e32 v149, v149, v155
	global_load_lds_dwordx4 v150, s[30:31]
	s_add_i32 m0, s101, s2
	v_add_u32_e32 v150, 0x40000, v150
	global_load_lds_dwordx4 v151, s[30:31]
	v_add_u32_e32 v151, 0x40000, v151

; __device__ __forceinline__ s16x4 vtr(const LAS unsigned char* p) { return __builtin_bit_cast(s16x4, __builtin_amdgcn_ds_read_tr16_b64_v4i16((LAS s16x4*)p)); }
; template <int MODE, int NQ> ...
;     ...
;         stage_store<HASP, HASV>(st, lds + OFF_K + bsel * KBUF, lds + OFF_V + bsel * VBUF, tid);
;     ...
;             if (MODE != M_CMP1) {
;                 bf16x8 pf[4]; pf[0] = pack8(s0, 0); pf[1] = pack8(s0, 8); pf[2] = pack8(s1, 0); pf[3] = pack8(s1, 8);
;                 if (MODE == M_SEL) { const bf16x8 z = {0, 0, 0, 0, 0, 0, 0, 0};
; #pragma unroll
;                     for (int i = 0; i < 4; ++i) pf[i] = lv ? pf[i] : z; }
; #pragma unroll
;                 for (int ks = 0; ks < 4; ++ks)
; #pragma unroll
;                     for (int db = 0; db < 4; ++db) {
;                         const s16x4 lo = vtr(vb + (16 * ks) * VP + db * 64), hv = vtr(vb + (16 * ks + 8) * VP + db * 64);
;                         const bf16x8 vf = {lo[0], lo[1], lo[2], lo[3], hv[0], hv[1], hv[2], hv[3]};
;                         O[db] = __builtin_amdgcn_mfma_f32_32x32x16_bf16(vf, pf[ks], O[db], 0, 0, 0);
;                     }
.LBB0_969:
.Lst_mla_mid:
	s_mulk_i32 s65, 0x5000
	v_add_u32_e32 v206, s65, v175
	v_cvt_pk_bf16_f32 v94, v191, v193
	v_cvt_pk_bf16_f32 v95, v195, v197
	ds_read_b64_tr_b16 v[198:199], v206 offset:51200
	ds_read_b64_tr_b16 v[200:201], v206 offset:53760
	v_cvt_pk_bf16_f32 v96, v190, v192
	v_cvt_pk_bf16_f32 v97, v194, v196
	ds_read_b64_tr_b16 v[190:191], v206 offset:51264
	ds_read_b64_tr_b16 v[194:195], v206 offset:51328
	ds_read_b64_tr_b16 v[202:203], v206 offset:51392
	ds_read_b64_tr_b16 v[192:193], v206 offset:53824
	ds_read_b64_tr_b16 v[196:197], v206 offset:53888
	ds_read_b64_tr_b16 v[204:205], v206 offset:53952
	s_waitcnt lgkmcnt(6)
	v_mfma_f32_32x32x16_bf16 v[50:65], v[198:201], v[94:97], v[50:65]
	v_cvt_pk_bf16_f32 v89, v89, v90
	v_cvt_pk_bf16_f32 v90, v91, v92
	v_cvt_pk_bf16_f32 v88, v87, v88
	v_cvt_pk_bf16_f32 v91, v80, v81
	v_cvt_pk_bf16_f32 v80, v82, v67
	v_cvt_pk_bf16_f32 v81, v68, v83
	v_cvt_pk_bf16_f32 v82, v84, v85
	s_waitcnt lgkmcnt(2)
	v_mfma_f32_32x32x16_bf16 v[34:49], v[190:193], v[94:97], v[34:49]
	ds_read_b64_tr_b16 v[190:191], v206 offset:56320
	ds_read_b64_tr_b16 v[192:193], v206 offset:58880
	v_cvt_pk_bf16_f32 v83, v72, v86
	v_add_u32_e32 v67, 0xc800, v206
	v_cvt_pk_bf16_f32 v68, v69, v70
	v_cvt_pk_bf16_f32 v69, v71, v75
	v_cvt_pk_bf16_f32 v70, v76, v78
	v_cvt_pk_bf16_f32 v71, v77, v79
	s_waitcnt lgkmcnt(3)
	v_mfma_f32_32x32x16_bf16 v[18:33], v[194:197], v[94:97], v[18:33]
	s_waitcnt lgkmcnt(2)
	v_mfma_f32_32x32x16_bf16 v[2:17], v[202:205], v[94:97], v[2:17]
	ds_read_b64_tr_b16 v[92:93], v206 offset:56384
	ds_read_b64_tr_b16 v[194:195], v206 offset:56448
	ds_read_b64_tr_b16 v[198:199], v206 offset:56512
	ds_read_b64_tr_b16 v[94:95], v206 offset:58944
	ds_read_b64_tr_b16 v[196:197], v206 offset:59008
	ds_read_b64_tr_b16 v[200:201], v206 offset:59072
	s_waitcnt lgkmcnt(6)
	v_mfma_f32_32x32x16_bf16 v[50:65], v[190:193], v[88:91], v[50:65]
	s_waitcnt lgkmcnt(2)
	v_mfma_f32_32x32x16_bf16 v[34:49], v[92:95], v[88:91], v[34:49]
	ds_read_b64_tr_b16 v[92:93], v206 offset:61440
	ds_read_b64_tr_b16 v[94:95], v206 offset:64000
	s_waitcnt lgkmcnt(3)
	v_mfma_f32_32x32x16_bf16 v[18:33], v[194:197], v[88:91], v[18:33]
	s_waitcnt lgkmcnt(2)
	v_mfma_f32_32x32x16_bf16 v[2:17], v[198:201], v[88:91], v[2:17]
	ds_read_b64_tr_b16 v[84:85], v206 offset:61504
	ds_read_b64_tr_b16 v[88:89], v206 offset:61568
	ds_read_b64_tr_b16 v[190:191], v206 offset:61632
	ds_read_b64_tr_b16 v[86:87], v206 offset:64064
	ds_read_b64_tr_b16 v[90:91], v206 offset:64128
	ds_read_b64_tr_b16 v[192:193], v206 offset:64192
	s_waitcnt lgkmcnt(6)
	v_mfma_f32_32x32x16_bf16 v[50:65], v[92:95], v[80:83], v[50:65]
	s_waitcnt lgkmcnt(2)
	v_mfma_f32_32x32x16_bf16 v[34:49], v[84:87], v[80:83], v[34:49]
	ds_read_b64_tr_b16 v[84:85], v67 offset:15360
	ds_read_b64_tr_b16 v[86:87], v67 offset:17920
	s_waitcnt lgkmcnt(3)
	v_mfma_f32_32x32x16_bf16 v[18:33], v[88:91], v[80:83], v[18:33]
	s_waitcnt lgkmcnt(2)
	v_mfma_f32_32x32x16_bf16 v[2:17], v[190:193], v[80:83], v[2:17]
	ds_read_b64_tr_b16 v[76:77], v67 offset:15424
	ds_read_b64_tr_b16 v[80:81], v67 offset:15488
	ds_read_b64_tr_b16 v[88:89], v67 offset:15552
	ds_read_b64_tr_b16 v[78:79], v67 offset:17984
	ds_read_b64_tr_b16 v[82:83], v67 offset:18048
	ds_read_b64_tr_b16 v[90:91], v67 offset:18112
	v_add_f32_e32 v67, v73, v74
	v_fmac_f32_e32 v67, v188, v66
	v_mov_b32_e32 v188, v67
	s_waitcnt lgkmcnt(6)
	v_mfma_f32_32x32x16_bf16 v[50:65], v[84:87], v[68:71], v[50:65]
	s_waitcnt lgkmcnt(2)
	v_mfma_f32_32x32x16_bf16 v[34:49], v[76:79], v[68:71], v[34:49]
	s_waitcnt lgkmcnt(1)
	v_mfma_f32_32x32x16_bf16 v[18:33], v[80:83], v[68:71], v[18:33]
	s_waitcnt lgkmcnt(0)
	v_mfma_f32_32x32x16_bf16 v[2:17], v[88:91], v[68:71], v[2:17]
	s_branch .LBB0_971
.LBB0_970:
.Lst_mla_skip:
	v_mov_b32_e32 v189, v190
